# P2 gdn_prep lowT / a_intra stage: 28 exec-masked serialized gc/beta LDS reads hoisted and issued together
# baseline (speedup 1.0000x reference)
; DEV unsigned cvt_pk_bf16(float lo, float hi) { const f32x2_t v = {lo, hi}; const bf16x2_t b = __builtin_convertvector(v, bf16x2_t); return __builtin_bit_cast(unsigned, b); }
; DEV bf16_t f2bf(float f) { return (bf16_t)(cvt_pk_bf16(f, 0.f) & 0xffffu); }
; DEV float bf2f(unsigned b) { return __uint_as_float(b << 16); }
; DEV float bflo(unsigned u) { return __uint_as_float(u << 16); }
; DEV float bfhi(unsigned u) { return __uint_as_float(u & 0xffff0000u); }
; DEV void gdn_prep_chunk(const Params& p, int item, unsigned char* lds) {
;     ...
;         const float glast = gcs[63];
;         if (tid == 0) *gE = __expf(glast);
; #pragma unroll
;         for (int i = 0; i < 4; ++i) {
;             const int ci = tid + 256 * i, t = ci >> 4, cc = (ci & 15) * 8;
;             const uint4 u = *(const uint4*)(qs + t * QS + cc);
;             const float e = __expf(gcs[t]);
;             uint4 o; o.x = cvt_pk_bf16(bflo(u.x) * e, bfhi(u.x) * e); o.y = cvt_pk_bf16(bflo(u.y) * e, bfhi(u.y) * e);
;             o.z = cvt_pk_bf16(bflo(u.z) * e, bfhi(u.z) * e); o.w = cvt_pk_bf16(bflo(u.w) * e, bfhi(u.w) * e);
;             *(uint4*)(gQ + (cc >> 5) * 2048 + t * 32 + (cc & 31)) = o;
;         }
;         const float dk = __expf(glast - gcs[lane]);
; #pragma unroll 8
;         for (int i = 0; i < 32; ++i) { const int d = wid * 32 + i; gKT[(lane >> 5) * 4096 + d * 32 + (lane & 31)] = f2bf(bf2f(ks[lane * QS + d]) * dk);     }
.LBB0_511:
	s_or_b64 exec, exec, s[4:5]
	v_lshlrev_b32_e32 v3, 4, v130
	v_and_b32_e32 v4, 0xf0, v3
	v_add_u32_e32 v12, s39, v4
	v_ashrrev_i32_e32 v13, 4, v130
	v_mad_u64_u32 v[4:5], s[34:35], v13, s57, v[12:13]
	v_lshl_add_u32 v9, v13, 2, s39
	ds_read_b128 v[4:7], v4
	ds_read_b32 v10, v9 offset:52224
	s_lshl_b64 s[4:5], s[30:31], 14
	s_add_u32 s6, s45, s4
	v_lshlrev_b32_e32 v8, 10, v130
	s_addc_u32 s7, s46, s5
	v_and_b32_e32 v142, 0x3000, v8
	v_lshl_add_u64 v[8:9], s[6:7], 0, v[142:143]
	v_and_b32_e32 v142, 48, v3
	s_waitcnt lgkmcnt(0)
	v_mul_f32_e32 v3, 0x3fb8aa3b, v10
	v_lshl_add_u64 v[14:15], v[8:9], 0, v[142:143]
	v_exp_f32_e32 v8, v3
	v_lshlrev_b32_e32 v10, 16, v4
	v_and_b32_e32 v11, 0xffff0000, v4
	v_mov_b32_e32 v3, s39
	v_pk_mul_f32 v[10:11], v[8:9], v[10:11] op_sel_hi:[0,1]
	v_cvt_pk_bf16_f32 v4, v10, v11
	v_lshlrev_b32_e32 v10, 16, v5
	v_and_b32_e32 v11, 0xffff0000, v5
	v_pk_mul_f32 v[10:11], v[8:9], v[10:11] op_sel_hi:[0,1]
	v_cvt_pk_bf16_f32 v5, v10, v11
	v_lshlrev_b32_e32 v10, 16, v6
	v_and_b32_e32 v11, 0xffff0000, v6
	v_pk_mul_f32 v[10:11], v[8:9], v[10:11] op_sel_hi:[0,1]
	v_cvt_pk_bf16_f32 v6, v10, v11
	v_lshlrev_b32_e32 v10, 16, v7
	v_and_b32_e32 v11, 0xffff0000, v7
	v_add_u32_e32 v7, 0x100, v130
	v_ashrrev_i32_e32 v19, 4, v7
	v_pk_mul_f32 v[16:17], v[8:9], v[10:11] op_sel_hi:[0,1]
	v_mad_u64_u32 v[8:9], s[6:7], v19, s57, v[12:13]
	v_lshl_add_u32 v7, v19, 2, s39
	ds_read_b128 v[8:11], v8
	ds_read_b32 v18, v7 offset:52224
	v_cvt_pk_bf16_f32 v7, v16, v17
	v_lshlrev_b32_e32 v16, 5, v13
	v_ashrrev_i32_e32 v17, 31, v16
	v_lshl_add_u64 v[16:17], v[16:17], 1, v[14:15]
	s_waitcnt lgkmcnt(0)
	v_mul_f32_e32 v13, 0x3fb8aa3b, v18
	v_exp_f32_e32 v18, v13
	global_store_dwordx4 v[16:17], v[4:7], off
	v_mad_u32_u24 v20, v34, s57, v3
	v_lshl_add_u32 v3, v131, 6, v20
	v_lshlrev_b32_e32 v4, 16, v8
	v_and_b32_e32 v5, 0xffff0000, v8
	v_lshlrev_b32_e32 v6, 16, v9
	v_and_b32_e32 v7, 0xffff0000, v9
	v_pk_mul_f32 v[4:5], v[18:19], v[4:5] op_sel_hi:[0,1]
	v_pk_mul_f32 v[6:7], v[18:19], v[6:7] op_sel_hi:[0,1]
	v_cvt_pk_bf16_f32 v4, v4, v5
	v_cvt_pk_bf16_f32 v5, v6, v7
	v_lshlrev_b32_e32 v6, 16, v10
	v_and_b32_e32 v7, 0xffff0000, v10
	v_pk_mul_f32 v[6:7], v[18:19], v[6:7] op_sel_hi:[0,1]
	v_cvt_pk_bf16_f32 v6, v6, v7
	v_add_u32_e32 v7, 0x200, v130
	v_lshlrev_b32_e32 v8, 16, v11
	v_and_b32_e32 v9, 0xffff0000, v11
	v_ashrrev_i32_e32 v13, 4, v7
	v_pk_mul_f32 v[16:17], v[18:19], v[8:9] op_sel_hi:[0,1]
	v_mad_u64_u32 v[8:9], s[6:7], v13, s57, v[12:13]
	v_lshl_add_u32 v7, v13, 2, s39
	ds_read_b128 v[8:11], v8
	ds_read_b32 v18, v7 offset:52224
	v_cvt_pk_bf16_f32 v7, v16, v17
	v_lshlrev_b32_e32 v16, 5, v19
	v_ashrrev_i32_e32 v17, 31, v16
	v_lshl_add_u64 v[16:17], v[16:17], 1, v[14:15]
	s_waitcnt lgkmcnt(0)
	v_mul_f32_e32 v18, 0x3fb8aa3b, v18
	v_exp_f32_e32 v18, v18
	global_store_dwordx4 v[16:17], v[4:7], off
	v_and_b32_e32 v38, 31, v130
	s_add_u32 s4, s47, s4
	v_lshlrev_b32_e32 v4, 16, v8
	v_and_b32_e32 v5, 0xffff0000, v8
	v_lshlrev_b32_e32 v6, 16, v9
	v_and_b32_e32 v7, 0xffff0000, v9
	v_pk_mul_f32 v[4:5], v[18:19], v[4:5] op_sel_hi:[0,1]
	v_pk_mul_f32 v[6:7], v[18:19], v[6:7] op_sel_hi:[0,1]
	v_cvt_pk_bf16_f32 v4, v4, v5
	v_cvt_pk_bf16_f32 v5, v6, v7
	v_lshlrev_b32_e32 v6, 16, v10
	v_and_b32_e32 v7, 0xffff0000, v10
	v_lshlrev_b32_e32 v8, 16, v11
	v_and_b32_e32 v9, 0xffff0000, v11
	v_pk_mul_f32 v[6:7], v[18:19], v[6:7] op_sel_hi:[0,1]
	v_pk_mul_f32 v[8:9], v[18:19], v[8:9] op_sel_hi:[0,1]
	v_cvt_pk_bf16_f32 v6, v6, v7
	v_cvt_pk_bf16_f32 v7, v8, v9
	v_lshlrev_b32_e32 v8, 5, v13
	v_ashrrev_i32_e32 v9, 31, v8
	v_lshl_add_u64 v[16:17], v[8:9], 1, v[14:15]
	v_add_u32_e32 v8, 0x300, v130
	v_ashrrev_i32_e32 v19, 4, v8
	v_mad_u64_u32 v[8:9], s[6:7], v19, s57, v[12:13]
	v_lshl_add_u32 v9, v19, 2, s39
	ds_read_b32 v18, v9 offset:52224
	v_lshl_add_u32 v12, v34, 2, s39
	ds_read_b128 v[8:11], v8
	ds_read_b32 v21, v12 offset:52224
	ds_read_b64 v[12:13], v3 offset:17408
	global_store_dwordx4 v[16:17], v[4:7], off
	s_addc_u32 s5, s48, s5
	s_waitcnt lgkmcnt(3)
	v_mul_f32_e32 v3, 0x3fb8aa3b, v18
	v_exp_f32_e32 v18, v3
	s_waitcnt lgkmcnt(2)
	v_lshlrev_b32_e32 v4, 16, v8
	v_and_b32_e32 v5, 0xffff0000, v8
	v_lshlrev_b32_e32 v6, 16, v9
	v_and_b32_e32 v7, 0xffff0000, v9
	v_pk_mul_f32 v[4:5], v[18:19], v[4:5] op_sel_hi:[0,1]
	v_pk_mul_f32 v[6:7], v[18:19], v[6:7] op_sel_hi:[0,1]
	v_cvt_pk_bf16_f32 v4, v4, v5
	v_cvt_pk_bf16_f32 v5, v6, v7
	v_lshlrev_b32_e32 v6, 16, v10
	v_and_b32_e32 v7, 0xffff0000, v10
	v_lshlrev_b32_e32 v8, 16, v11
	v_and_b32_e32 v9, 0xffff0000, v11
	s_waitcnt lgkmcnt(1)
	v_sub_f32_e32 v2, v2, v21
	v_pk_mul_f32 v[6:7], v[18:19], v[6:7] op_sel_hi:[0,1]
	v_pk_mul_f32 v[8:9], v[18:19], v[8:9] op_sel_hi:[0,1]
	v_mul_f32_e32 v2, 0x3fb8aa3b, v2
	v_cvt_pk_bf16_f32 v6, v6, v7
	v_cvt_pk_bf16_f32 v7, v8, v9
	v_lshlrev_b32_e32 v8, 5, v19
	v_exp_f32_e32 v2, v2
	v_ashrrev_i32_e32 v9, 31, v8
	v_lshl_add_u64 v[8:9], v[8:9], 1, v[14:15]
	v_lshlrev_b32_e32 v3, 7, v34
	global_store_dwordx4 v[8:9], v[4:7], off
	v_and_or_b32 v3, v3, s63, v38
	v_lshlrev_b32_e32 v22, 5, v131
	s_waitcnt lgkmcnt(0)
	v_and_b32_e32 v5, 0xffff0000, v13
	v_lshlrev_b32_e32 v4, 16, v13
	v_and_b32_e32 v7, 0xffff0000, v12
	v_lshlrev_b32_e32 v6, 16, v12
	v_pk_mul_f32 v[4:5], v[2:3], v[4:5] op_sel_hi:[0,1]
	v_pk_mul_f32 v[6:7], v[2:3], v[6:7] op_sel_hi:[0,1]
	v_cvt_pk_bf16_f32 v15, v4, s0
	v_lshl_add_u32 v4, v131, 10, v3
	v_cvt_pk_bf16_f32 v17, v6, s0
	v_or_b32_e32 v6, 32, v4
	v_cvt_pk_bf16_f32 v14, v5, s0
	v_cvt_pk_bf16_f32 v16, v7, s0
	v_or_b32_e32 v8, 64, v4
	v_or_b32_e32 v10, 0x60, v4
	v_ashrrev_i32_e32 v7, 31, v6
	v_ashrrev_i32_e32 v5, 31, v4
	v_ashrrev_i32_e32 v11, 31, v10
	v_ashrrev_i32_e32 v9, 31, v8
	v_lshl_add_u64 v[12:13], v[4:5], 1, s[4:5]
	v_lshl_add_u64 v[6:7], v[6:7], 1, s[4:5]
	v_or_b32_e32 v5, 4, v22
	v_lshl_add_u64 v[8:9], v[8:9], 1, s[4:5]
	v_lshl_add_u64 v[10:11], v[10:11], 1, s[4:5]
	global_store_short v[12:13], v17, off
	global_store_short v[6:7], v16, off
	global_store_short v[8:9], v15, off
	global_store_short v[10:11], v14, off
	v_lshl_add_u32 v6, v5, 1, v20
	ds_read_b64 v[6:7], v6 offset:17408
	v_or_b32_e32 v21, 8, v22
	v_or_b32_e32 v23, 12, v22
	v_or_b32_e32 v24, 16, v22
	v_lshl_add_u32 v8, v21, 1, v20
	s_waitcnt lgkmcnt(0)
; DEV bf16_t f2bf(float f) { return (bf16_t)(cvt_pk_bf16(f, 0.f) & 0xffffu); }
; DEV float bf2f(unsigned b) { return __uint_as_float(b << 16); }
; DEV void gdn_prep_chunk(const Params& p, int item, unsigned char* lds) {
;     ...
;         const float dk = __expf(glast - gcs[lane]);
; #pragma unroll 8
;         for (int i = 0; i < 32; ++i) { const int d = wid * 32 + i; gKT[(lane >> 5) * 4096 + d * 32 + (lane & 31)] = f2bf(bf2f(ks[lane * QS + d]) * dk);     }
;     }
;     f32x4 kk[4], qk[4];
;     {
;         const int fr = lane & 15, fq = lane >> 4, it = wid;
;         bf16x8 kfi[4], qfi[4];
; #pragma unroll
;         for (int s = 0; s < 4; ++s) { kfi[s] = *(const bf16x8*)(ks + (it * 16 + fr) * QS + s * 32 + fq * 8); qfi[s] = *(const bf16x8*)(qs + (it * 16 + fr) * QS + s * 32 + fq * 8); }
; #pragma unroll
;         for (int jt = 0; jt < 4; ++jt) {
;             kk[jt] = (f32x4){0.f, 0.f, 0.f, 0.f}; qk[jt] = (f32x4){0.f, 0.f, 0.f, 0.f};
; #pragma unroll
;             for (int s = 0; s < 4; ++s) {
;                 const bf16x8 kfj = *(const bf16x8*)(ks + (jt * 16 + fr) * QS + s * 32 + fq * 8);
;                 kk[jt] = __builtin_amdgcn_mfma_f32_16x16x32_bf16(kfi[s], kfj, kk[jt], 0, 0, 0);
;                 qk[jt] = __builtin_amdgcn_mfma_f32_16x16x32_bf16(kfj, qfi[s], qk[jt], 0, 0, 0);
;             }
;         }
;     }
	v_and_b32_e32 v15, 0xffff0000, v7
	v_lshlrev_b32_e32 v14, 16, v7
	v_and_b32_e32 v7, 0xffff0000, v6
	v_lshlrev_b32_e32 v6, 16, v6
	v_lshl_add_u32 v10, v23, 1, v20
	v_lshl_add_u32 v12, v24, 1, v20
	v_pk_mul_f32 v[6:7], v[2:3], v[6:7] op_sel_hi:[0,1]
	ds_read_b64 v[8:9], v8 offset:17408
	ds_read_b64 v[10:11], v10 offset:17408
	ds_read_b64 v[12:13], v12 offset:17408
	v_pk_mul_f32 v[14:15], v[2:3], v[14:15] op_sel_hi:[0,1]
	v_cvt_pk_bf16_f32 v28, v6, s0
	v_lshl_add_u32 v6, v5, 5, v3
	v_cvt_pk_bf16_f32 v26, v14, s0
	v_cvt_pk_bf16_f32 v27, v7, s0
	v_or_b32_e32 v14, 0xa0, v4
	v_or_b32_e32 v16, 0xc0, v4
	v_or_b32_e32 v18, 0xe0, v4
	v_ashrrev_i32_e32 v7, 31, v6
	v_cvt_pk_bf16_f32 v25, v15, s0
	v_ashrrev_i32_e32 v19, 31, v18
	v_ashrrev_i32_e32 v17, 31, v16
	v_ashrrev_i32_e32 v15, 31, v14
	v_lshl_add_u64 v[6:7], v[6:7], 1, s[4:5]
	v_lshl_add_u64 v[14:15], v[14:15], 1, s[4:5]
	v_lshl_add_u64 v[16:17], v[16:17], 1, s[4:5]
	v_lshl_add_u64 v[18:19], v[18:19], 1, s[4:5]
	global_store_short v[6:7], v28, off
	global_store_short v[14:15], v27, off
	global_store_short v[16:17], v26, off
	global_store_short v[18:19], v25, off
	s_waitcnt lgkmcnt(2)
	v_and_b32_e32 v7, 0xffff0000, v9
	v_lshlrev_b32_e32 v6, 16, v9
	v_and_b32_e32 v9, 0xffff0000, v8
	v_lshlrev_b32_e32 v8, 16, v8
	v_pk_mul_f32 v[6:7], v[2:3], v[6:7] op_sel_hi:[0,1]
	v_pk_mul_f32 v[8:9], v[2:3], v[8:9] op_sel_hi:[0,1]
	v_cvt_pk_bf16_f32 v18, v6, s0
	v_lshl_add_u32 v6, v21, 5, v3
	v_cvt_pk_bf16_f32 v5, v7, s0
	v_cvt_pk_bf16_f32 v25, v8, s0
	v_or_b32_e32 v8, 0x120, v4
	v_or_b32_e32 v14, 0x140, v4
	v_or_b32_e32 v16, 0x160, v4
	v_ashrrev_i32_e32 v7, 31, v6
	v_cvt_pk_bf16_f32 v19, v9, s0
	v_ashrrev_i32_e32 v17, 31, v16
	v_ashrrev_i32_e32 v15, 31, v14
	v_ashrrev_i32_e32 v9, 31, v8
	v_lshl_add_u64 v[6:7], v[6:7], 1, s[4:5]
	v_lshl_add_u64 v[8:9], v[8:9], 1, s[4:5]
	v_lshl_add_u64 v[14:15], v[14:15], 1, s[4:5]
	v_lshl_add_u64 v[16:17], v[16:17], 1, s[4:5]
	global_store_short v[6:7], v25, off
	global_store_short v[8:9], v19, off
	global_store_short v[14:15], v18, off
	global_store_short v[16:17], v5, off
	s_waitcnt lgkmcnt(1)
	v_and_b32_e32 v7, 0xffff0000, v11
	v_lshlrev_b32_e32 v6, 16, v11
	v_and_b32_e32 v9, 0xffff0000, v10
	v_lshlrev_b32_e32 v8, 16, v10
	v_pk_mul_f32 v[6:7], v[2:3], v[6:7] op_sel_hi:[0,1]
	v_pk_mul_f32 v[8:9], v[2:3], v[8:9] op_sel_hi:[0,1]
	v_cvt_pk_bf16_f32 v16, v6, s0
	v_lshl_add_u32 v6, v23, 5, v3
	v_cvt_pk_bf16_f32 v5, v7, s0
	v_cvt_pk_bf16_f32 v18, v8, s0
	v_or_b32_e32 v8, 0x1a0, v4
	v_or_b32_e32 v10, 0x1c0, v4
	v_or_b32_e32 v14, 0x1e0, v4
	v_ashrrev_i32_e32 v7, 31, v6
	v_cvt_pk_bf16_f32 v17, v9, s0
	v_ashrrev_i32_e32 v15, 31, v14
	v_ashrrev_i32_e32 v11, 31, v10
	v_ashrrev_i32_e32 v9, 31, v8
	v_lshl_add_u64 v[6:7], v[6:7], 1, s[4:5]
	v_lshl_add_u64 v[8:9], v[8:9], 1, s[4:5]
	v_lshl_add_u64 v[10:11], v[10:11], 1, s[4:5]
	v_lshl_add_u64 v[14:15], v[14:15], 1, s[4:5]
	global_store_short v[6:7], v18, off
	global_store_short v[8:9], v17, off
	global_store_short v[10:11], v16, off
	global_store_short v[14:15], v5, off
	s_waitcnt lgkmcnt(0)
	v_and_b32_e32 v7, 0xffff0000, v13
	v_lshlrev_b32_e32 v6, 16, v13
	v_and_b32_e32 v9, 0xffff0000, v12
	v_lshlrev_b32_e32 v8, 16, v12
	v_pk_mul_f32 v[6:7], v[2:3], v[6:7] op_sel_hi:[0,1]
	v_pk_mul_f32 v[8:9], v[2:3], v[8:9] op_sel_hi:[0,1]
	v_cvt_pk_bf16_f32 v14, v6, s0
	v_lshl_add_u32 v6, v24, 5, v3
	v_cvt_pk_bf16_f32 v5, v7, s0
	v_cvt_pk_bf16_f32 v16, v8, s0
	v_or_b32_e32 v8, 0x220, v4
	v_or_b32_e32 v10, 0x240, v4
	v_or_b32_e32 v12, 0x260, v4
	v_ashrrev_i32_e32 v7, 31, v6
	v_cvt_pk_bf16_f32 v15, v9, s0
	v_ashrrev_i32_e32 v13, 31, v12
	v_ashrrev_i32_e32 v11, 31, v10
	v_ashrrev_i32_e32 v9, 31, v8
	v_lshl_add_u64 v[6:7], v[6:7], 1, s[4:5]
	v_lshl_add_u64 v[8:9], v[8:9], 1, s[4:5]
	v_lshl_add_u64 v[10:11], v[10:11], 1, s[4:5]
	v_lshl_add_u64 v[12:13], v[12:13], 1, s[4:5]
	global_store_short v[6:7], v16, off
	global_store_short v[8:9], v15, off
	global_store_short v[10:11], v14, off
	global_store_short v[12:13], v5, off
	v_or_b32_e32 v5, 20, v22
	v_lshl_add_u32 v6, v5, 1, v20
	v_or_b32_e32 v35, 24, v22
	ds_read_b64 v[14:15], v6 offset:17408
	v_lshl_add_u32 v6, v35, 1, v20
	v_or_b32_e32 v44, 28, v22
	v_lshl_add_u32 v7, v44, 1, v20
	ds_read_b64 v[36:37], v6 offset:17408
	ds_read_b64 v[82:83], v7 offset:17408
	v_and_b32_e32 v145, 15, v130
	v_lshlrev_b32_e32 v45, 4, v131
	v_and_b32_e32 v6, 48, v34
	v_or_b32_e32 v39, v45, v145
	v_add_u32_e32 v10, s39, v6
	v_mad_u64_u32 v[26:27], s[6:7], v39, s57, v[10:11]
	ds_read_b128 v[6:9], v26 offset:17408
	v_mad_u32_u24 v90, v145, s57, v10
	ds_read_b128 v[10:13], v90 offset:17408
	s_waitcnt lgkmcnt(4)
	v_and_b32_e32 v23, 0xffff0000, v15
	v_lshlrev_b32_e32 v22, 16, v15
	v_and_b32_e32 v25, 0xffff0000, v14
	v_lshlrev_b32_e32 v24, 16, v14
	ds_read_b128 v[40:43], v26
	ds_read_b128 v[46:49], v26 offset:17472
	ds_read_b128 v[14:17], v90 offset:17472
	ds_read_b128 v[50:53], v26 offset:64
	ds_read_b128 v[54:57], v26 offset:17536
	s_waitcnt lgkmcnt(5)
	v_mfma_f32_16x16x32_bf16 v[18:21], v[6:9], v[10:13], 0
	v_mul_f32_e64 v24, v2, v24
	v_mul_f32_e64 v25, v2, v25
	v_pk_mul_f32 v[22:23], v[2:3], v[22:23] op_sel_hi:[0,1]
	v_cvt_pk_bf16_f32 v74, v23, s0
	s_waitcnt lgkmcnt(4)
	v_mfma_f32_16x16x32_bf16 v[10:13], v[10:13], v[40:43], 0
	v_cvt_pk_bf16_f32 v75, v22, s0
	v_cvt_pk_bf16_f32 v76, v25, s0
	v_cvt_pk_bf16_f32 v77, v24, s0
	ds_read_b128 v[22:25], v90 offset:17536
	s_waitcnt lgkmcnt(3)
	v_mfma_f32_16x16x32_bf16 v[18:21], v[46:49], v[14:17], v[18:21]
	v_lshl_add_u32 v70, v5, 5, v3
	v_or_b32_e32 v72, 0x2a0, v4
	v_ashrrev_i32_e32 v71, 31, v70
	s_waitcnt lgkmcnt(2)
; DEV bf16_t f2bf(float f) { return (bf16_t)(cvt_pk_bf16(f, 0.f) & 0xffffu); }
; DEV float bf2f(unsigned b) { return __uint_as_float(b << 16); }
; DEV void gdn_prep_chunk(const Params& p, int item, unsigned char* lds) {
;     ...
;         for (int i = 0; i < 32; ++i) { const int d = wid * 32 + i; gKT[(lane >> 5) * 4096 + d * 32 + (lane & 31)] = f2bf(bf2f(ks[lane * QS + d]) * dk);     }
;     }
;     f32x4 kk[4], qk[4];
;     {
;         const int fr = lane & 15, fq = lane >> 4, it = wid;
;         bf16x8 kfi[4], qfi[4];
; #pragma unroll
;         for (int s = 0; s < 4; ++s) { kfi[s] = *(const bf16x8*)(ks + (it * 16 + fr) * QS + s * 32 + fq * 8); qfi[s] = *(const bf16x8*)(qs + (it * 16 + fr) * QS + s * 32 + fq * 8); }
; #pragma unroll
;         for (int jt = 0; jt < 4; ++jt) {
;             kk[jt] = (f32x4){0.f, 0.f, 0.f, 0.f}; qk[jt] = (f32x4){0.f, 0.f, 0.f, 0.f};
; #pragma unroll
;             for (int s = 0; s < 4; ++s) {
;                 const bf16x8 kfj = *(const bf16x8*)(ks + (jt * 16 + fr) * QS + s * 32 + fq * 8);
;                 kk[jt] = __builtin_amdgcn_mfma_f32_16x16x32_bf16(kfi[s], kfj, kk[jt], 0, 0, 0);
;                 qk[jt] = __builtin_amdgcn_mfma_f32_16x16x32_bf16(kfj, qfi[s], qk[jt], 0, 0, 0);
;             }
;         }
;     }
;     __syncthreads();
	v_mfma_f32_16x16x32_bf16 v[10:13], v[14:17], v[50:53], v[10:13]
	ds_read_b128 v[58:61], v26 offset:128
	ds_read_b128 v[62:65], v26 offset:17600
	ds_read_b128 v[14:17], v90 offset:17600
	ds_read_b128 v[66:69], v26 offset:192
	v_ashrrev_i32_e32 v73, 31, v72
	s_waitcnt lgkmcnt(4)
	v_mfma_f32_16x16x32_bf16 v[18:21], v[54:57], v[22:25], v[18:21]
	v_lshl_add_u64 v[70:71], v[70:71], 1, s[4:5]
	v_lshl_add_u64 v[72:73], v[72:73], 1, s[4:5]
	v_or_b32_e32 v78, 0x360, v4
	s_waitcnt lgkmcnt(3)
	v_mfma_f32_16x16x32_bf16 v[10:13], v[22:25], v[58:61], v[10:13]
	v_or_b32_e32 v22, 0x2c0, v4
	v_or_b32_e32 v24, 0x2e0, v4
	v_ashrrev_i32_e32 v25, 31, v24
	s_waitcnt lgkmcnt(1)
	v_mfma_f32_16x16x32_bf16 v[30:33], v[62:65], v[14:17], v[18:21]
	v_ashrrev_i32_e32 v23, 31, v22
	v_lshl_add_u64 v[22:23], v[22:23], 1, s[4:5]
	v_lshl_add_u64 v[24:25], v[24:25], 1, s[4:5]
	ds_read_b128 v[18:21], v90 offset:21760
	s_waitcnt lgkmcnt(1)
	v_mfma_f32_16x16x32_bf16 v[26:29], v[14:17], v[66:69], v[10:13]
	v_ashrrev_i32_e32 v79, 31, v78
	v_lshl_add_u64 v[88:89], v[78:79], 1, s[4:5]
	v_lshrrev_b32_e32 v34, 2, v34
	ds_read_b128 v[10:13], v90 offset:21824
	s_waitcnt lgkmcnt(1)
	v_mfma_f32_16x16x32_bf16 v[14:17], v[6:9], v[18:21], 0
	global_store_short v[70:71], v77, off
	global_store_short v[72:73], v76, off
	global_store_short v[22:23], v75, off
	global_store_short v[24:25], v74, off
	ds_read_b128 v[22:25], v90 offset:21888
	v_mfma_f32_16x16x32_bf16 v[18:21], v[18:21], v[40:43], 0
	v_and_b32_e32 v71, 0xffff0000, v37
	v_lshlrev_b32_e32 v70, 16, v37
	v_pk_mul_f32 v[70:71], v[2:3], v[70:71] op_sel_hi:[0,1]
	s_waitcnt lgkmcnt(1)
	v_mfma_f32_16x16x32_bf16 v[14:17], v[46:49], v[10:13], v[14:17]
	v_cvt_pk_bf16_f32 v5, v71, s0
	v_cvt_pk_bf16_f32 v91, v70, s0
	v_or_b32_e32 v74, 0x320, v4
	v_mfma_f32_16x16x32_bf16 v[10:13], v[10:13], v[50:53], v[18:21]
	v_or_b32_e32 v76, 0x340, v4
	v_ashrrev_i32_e32 v77, 31, v76
	v_ashrrev_i32_e32 v75, 31, v74
	ds_read_b128 v[18:21], v90 offset:21952
	s_waitcnt lgkmcnt(1)
	v_mfma_f32_16x16x32_bf16 v[14:17], v[54:57], v[22:25], v[14:17]
	v_and_b32_e32 v37, 0xffff0000, v36
	v_lshlrev_b32_e32 v36, 16, v36
	v_lshl_add_u64 v[84:85], v[74:75], 1, s[4:5]
	v_mfma_f32_16x16x32_bf16 v[10:13], v[22:25], v[58:61], v[10:13]
	v_lshl_add_u64 v[86:87], v[76:77], 1, s[4:5]
	ds_read_b128 v[74:77], v90 offset:26240
	v_pk_mul_f32 v[36:37], v[2:3], v[36:37] op_sel_hi:[0,1]
	s_waitcnt lgkmcnt(1)
	v_mfma_f32_16x16x32_bf16 v[22:25], v[62:65], v[18:21], v[14:17]
	v_cvt_pk_bf16_f32 v80, v36, s0
	v_lshl_add_u32 v36, v35, 5, v3
	v_cvt_pk_bf16_f32 v92, v37, s0
	ds_read_b128 v[14:17], v90 offset:26112
	v_mfma_f32_16x16x32_bf16 v[18:21], v[18:21], v[66:69], v[10:13]
	v_ashrrev_i32_e32 v37, 31, v36
	v_lshl_add_u64 v[36:37], v[36:37], 1, s[4:5]
	global_store_short v[36:37], v80, off
	ds_read_b128 v[10:13], v90 offset:26176
	s_waitcnt lgkmcnt(1)
	v_mfma_f32_16x16x32_bf16 v[70:73], v[6:9], v[14:17], 0
	ds_read_b128 v[78:81], v90 offset:26304
	global_store_short v[84:85], v92, off
	global_store_short v[86:87], v91, off
	global_store_short v[88:89], v5, off
	v_and_b32_e32 v37, 0xffff0000, v83
	v_mfma_f32_16x16x32_bf16 v[14:17], v[14:17], v[40:43], 0
	v_lshlrev_b32_e32 v36, 16, v83
	v_pk_mul_f32 v[36:37], v[2:3], v[36:37] op_sel_hi:[0,1]
	v_cvt_pk_bf16_f32 v35, v37, s0
	s_waitcnt lgkmcnt(1)
	v_mfma_f32_16x16x32_bf16 v[70:73], v[46:49], v[10:13], v[70:73]
	v_mfma_f32_16x16x32_bf16 v[10:13], v[10:13], v[50:53], v[14:17]
	v_mfma_f32_16x16x32_bf16 v[14:17], v[54:57], v[74:77], v[70:73]
	s_nop 5
	v_and_b32_e32 v71, 0xffff0000, v82
	v_lshlrev_b32_e32 v70, 16, v82
	v_pk_mul_f32 v[82:83], v[2:3], v[70:71] op_sel_hi:[0,1]
	ds_read_b128 v[70:73], v90 offset:30464
	v_mfma_f32_16x16x32_bf16 v[10:13], v[74:77], v[58:61], v[10:13]
	ds_read_b128 v[74:77], v90 offset:30528
	v_cvt_pk_bf16_f32 v82, v82, s0
	s_waitcnt lgkmcnt(2)
	v_mfma_f32_16x16x32_bf16 v[14:17], v[62:65], v[78:81], v[14:17]
	v_mfma_f32_16x16x32_bf16 v[10:13], v[78:81], v[66:69], v[10:13]
	v_cvt_pk_bf16_f32 v80, v36, s0
	v_lshl_add_u32 v36, v44, 5, v3
	v_or_b32_e32 v78, 0x3e0, v4
	s_waitcnt lgkmcnt(1)
	v_mfma_f32_16x16x32_bf16 v[6:9], v[6:9], v[70:73], 0
	v_ashrrev_i32_e32 v79, 31, v78
	v_ashrrev_i32_e32 v37, 31, v36
	v_cvt_pk_bf16_f32 v81, v83, s0
	v_mfma_f32_16x16x32_bf16 v[40:43], v[70:73], v[40:43], 0
	v_or_b32_e32 v70, 0x3a0, v4
	v_or_b32_e32 v72, 0x3c0, v4
	ds_read_b128 v[2:5], v90 offset:30592
	s_waitcnt lgkmcnt(1)
	v_mfma_f32_16x16x32_bf16 v[6:9], v[46:49], v[74:77], v[6:9]
	ds_read_b128 v[46:49], v90 offset:30656
	v_ashrrev_i32_e32 v71, 31, v70
	v_ashrrev_i32_e32 v73, 31, v72
	v_mfma_f32_16x16x32_bf16 v[40:43], v[74:77], v[50:53], v[40:43]
	v_lshl_add_u64 v[36:37], v[36:37], 1, s[4:5]
	v_lshl_add_u64 v[50:51], v[70:71], 1, s[4:5]
	global_store_short v[36:37], v82, off
	s_waitcnt lgkmcnt(1)
	v_mfma_f32_16x16x32_bf16 v[6:9], v[54:57], v[2:5], v[6:9]
	v_mov_b32_e32 v36, 0
	v_mfma_f32_16x16x32_bf16 v[2:5], v[2:5], v[58:61], v[40:43]
	s_nop 2
	v_lshl_add_u64 v[42:43], v[78:79], 1, s[4:5]
	v_lshl_add_u64 v[40:41], v[72:73], 1, s[4:5]
	global_store_short v[50:51], v81, off
	global_store_short v[40:41], v80, off
	global_store_short v[42:43], v35, off
	v_lshl_add_u32 v43, v145, 2, s39
	s_waitcnt lgkmcnt(0)
	v_mfma_f32_16x16x32_bf16 v[6:9], v[62:65], v[46:49], v[6:9]
	s_waitcnt vmcnt(63) expcnt(7) lgkmcnt(15)
	s_barrier
; DEV void gdn_prep_chunk(const Params& p, int item, unsigned char* lds) {
;     ...
;         const int fr = lane & 15, fq = lane >> 4, it = wid;
; #pragma unroll
;         for (int jt = 0; jt < 4; ++jt) {
;             const int j = jt * 16 + fr; const float gj = gcs[j];
;             f32x4 lv;
; #pragma unroll
;             for (int e = 0; e < 4; ++e) { const int i = it * 16 + fq * 4 + e; lv[e] = (i > j) ? bts[i] * kk[jt][e] * __expf(gcs[i] - gj) : 0.f; }
;             *(f32x4*)(lowT + j * 68 + it * 16 + fq * 4) = lv;
	v_mfma_f32_16x16x32_bf16 v[2:5], v[46:49], v[66:69], v[2:5]
	v_and_b32_e32 v78, 12, v34
	v_or_b32_e32 v79, v78, v45
	v_lshl_add_u32 v80, v79, 2, s39
	ds_read2st64_b32 v[82:83], v80 offset0:204 offset1:205
	v_and_b32_e32 v84, 12, v34
	v_or_b32_e32 v85, v84, v45
	v_lshl_add_u32 v86, v85, 2, s39
	v_add_u32_e32 v86, 8, v86
	ds_read2st64_b32 v[88:89], v86 offset0:204 offset1:205
	v_and_b32_e32 v90, 12, v34
	v_or_b32_e32 v91, v90, v45
	v_lshl_add_u32 v92, v91, 2, s39
	v_add_u32_e32 v92, 12, v92
	ds_read2st64_b32 v[94:95], v92 offset0:204 offset1:205
	v_and_b32_e32 v96, 12, v34
	v_lshl_add_u32 v97, v96, 2, s39
	ds_read_b32 v98, v97 offset:52224
	v_and_b32_e32 v99, 12, v34
	v_lshl_add_u32 v100, v99, 2, s39
	ds_read_b32 v101, v100 offset:52228
	v_and_b32_e32 v102, 12, v34
	v_lshl_add_u32 v103, v102, 2, s39
	ds_read_b32 v104, v103 offset:52232
	v_and_b32_e32 v105, 12, v34
	v_lshl_add_u32 v106, v105, 2, s39
	ds_read_b32 v107, v106 offset:52236
	v_and_b32_e32 v108, 12, v34
	v_or_b32_e32 v109, v108, v45
	v_lshl_add_u32 v110, v109, 2, s39
	ds_read2st64_b32 v[112:113], v110 offset0:204 offset1:205
	v_and_b32_e32 v114, 12, v34
	v_or_b32_e32 v115, v114, v45
	v_lshl_add_u32 v116, v115, 2, s39
	v_add_u32_e32 v116, 4, v116
	ds_read2st64_b32 v[118:119], v116 offset0:204 offset1:205
	v_and_b32_e32 v120, 12, v34
	v_or_b32_e32 v121, v120, v45
	v_lshl_add_u32 v122, v121, 2, s39
	v_add_u32_e32 v122, 8, v122
	ds_read2st64_b32 v[124:125], v122 offset0:204 offset1:205
	v_and_b32_e32 v126, 12, v34
	v_lshl_add_u32 v127, v126, 2, s39
	ds_read_b32 v128, v127 offset:52288
	v_and_b32_e32 v129, 12, v34
	v_lshl_add_u32 v189, v129, 2, s39
	ds_read_b32 v190, v189 offset:52292
	v_and_b32_e32 v191, 12, v34
	v_lshl_add_u32 v192, v191, 2, s39
	ds_read_b32 v193, v192 offset:52296
	v_and_b32_e32 v194, 12, v34
	v_lshl_add_u32 v195, v194, 2, s39
	ds_read_b32 v196, v195 offset:52300
	v_and_b32_e32 v197, 12, v34
	v_or_b32_e32 v198, v197, v45
	v_lshl_add_u32 v199, v198, 2, s39
	ds_read2st64_b32 v[200:201], v199 offset0:204 offset1:205
	v_and_b32_e32 v202, 12, v34
	v_or_b32_e32 v203, v202, v45
	v_lshl_add_u32 v204, v203, 2, s39
	v_add_u32_e32 v204, 4, v204
	ds_read2st64_b32 v[206:207], v204 offset0:204 offset1:205
	v_and_b32_e32 v208, 12, v34
	v_or_b32_e32 v209, v208, v45
	v_lshl_add_u32 v210, v209, 2, s39
	v_add_u32_e32 v210, 8, v210
	ds_read2st64_b32 v[212:213], v210 offset0:204 offset1:205
	v_and_b32_e32 v214, 12, v34
	v_lshl_add_u32 v215, v214, 2, s39
	ds_read_b32 v216, v215 offset:52352
	v_and_b32_e32 v217, 12, v34
	v_lshl_add_u32 v218, v217, 2, s39
	ds_read_b32 v219, v218 offset:52356
	v_and_b32_e32 v220, 12, v34
	v_lshl_add_u32 v221, v220, 2, s39
	ds_read_b32 v222, v221 offset:52360
	v_and_b32_e32 v223, 12, v34
	v_lshl_add_u32 v224, v223, 2, s39
	ds_read_b32 v225, v224 offset:52364
	v_and_b32_e32 v226, 12, v34
	v_or_b32_e32 v227, v226, v45
	v_lshl_add_u32 v228, v227, 2, s39
	ds_read2st64_b32 v[230:231], v228 offset0:204 offset1:205
	v_and_b32_e32 v232, 12, v34
	v_or_b32_e32 v233, v232, v45
	v_lshl_add_u32 v234, v233, 2, s39
	v_add_u32_e32 v234, 4, v234
	ds_read2st64_b32 v[236:237], v234 offset0:204 offset1:205
	v_and_b32_e32 v238, 12, v34
	v_or_b32_e32 v239, v238, v45
	v_lshl_add_u32 v240, v239, 2, s39
	v_add_u32_e32 v240, 8, v240
	ds_read2st64_b32 v[242:243], v240 offset0:204 offset1:205
	v_and_b32_e32 v244, 12, v34
	v_lshl_add_u32 v245, v244, 2, s39
	ds_read_b32 v246, v245 offset:52416
	v_and_b32_e32 v247, 12, v34
	v_lshl_add_u32 v248, v247, 2, s39
	ds_read_b32 v249, v248 offset:52420
	v_and_b32_e32 v250, 12, v34
	v_lshl_add_u32 v251, v250, 2, s39
	ds_read_b32 v146, v251 offset:52424
	v_and_b32_e32 v147, 12, v34
	v_lshl_add_u32 v148, v147, 2, s39
	ds_read_b32 v149, v148 offset:52428
	ds_read_b32 v46, v43 offset:52224
	v_and_b32_e32 v40, 12, v34
	v_or_b32_e32 v41, v40, v45
	v_cmp_gt_i32_e32 vcc, v41, v145
	v_mov_b32_e32 v34, 0
	s_and_saveexec_b64 s[4:5], vcc
	s_cbranch_execz .LBB0_513
	v_lshl_add_u32 v34, v41, 2, s39

; DEV void gdn_prep_chunk(const Params& p, int item, unsigned char* lds) {
;     ...
;             for (int e = 0; e < 4; ++e) { const int i = it * 16 + fq * 4 + e; lv[e] = (i > j) ? bts[i] * kk[jt][e] * __expf(gcs[i] - gj) : 0.f; }
	s_waitcnt lgkmcnt(0)
	v_sub_f32_e32 v34, v82, v46
	v_mul_f32_e32 v34, 0x3fb8aa3b, v34
	v_exp_f32_e32 v34, v34
	v_mul_f32_e32 v30, v30, v83
	v_mul_f32_e32 v34, v30, v34

; DEV void gdn_prep_chunk(const Params& p, int item, unsigned char* lds) {
;     ...
;             for (int e = 0; e < 4; ++e) { const int i = it * 16 + fq * 4 + e; lv[e] = (i > j) ? bts[i] * kk[jt][e] * __expf(gcs[i] - gj) : 0.f; }
.LBB0_515:
	s_or_b64 exec, exec, s[4:5]
	v_or_b32_e32 v42, 2, v41
	v_cmp_gt_i32_e32 vcc, v42, v145
	s_and_saveexec_b64 s[4:5], vcc
	s_cbranch_execz .LBB0_517
	v_lshl_add_u32 v30, v41, 2, s39
	v_add_u32_e32 v30, 8, v30

; DEV void gdn_prep_chunk(const Params& p, int item, unsigned char* lds) {
;     ...
;             for (int e = 0; e < 4; ++e) { const int i = it * 16 + fq * 4 + e; lv[e] = (i > j) ? bts[i] * kk[jt][e] * __expf(gcs[i] - gj) : 0.f; }
	s_waitcnt lgkmcnt(0)
	v_sub_f32_e32 v30, v88, v46
	v_mul_f32_e32 v30, 0x3fb8aa3b, v30
	v_exp_f32_e32 v30, v30
	v_mul_f32_e32 v31, v32, v89
	v_mul_f32_e32 v36, v31, v30
.LBB0_517:
	s_or_b64 exec, exec, s[4:5]
	v_or_b32_e32 v44, 3, v41
	v_cmp_gt_i32_e32 vcc, v44, v145
	v_mov_b32_e32 v47, 0
	v_mov_b32_e32 v37, 0
	s_and_saveexec_b64 s[4:5], vcc
	s_cbranch_execz .LBB0_519
	v_lshl_add_u32 v30, v41, 2, s39
	v_add_u32_e32 v30, 12, v30

; DEV void gdn_prep_chunk(const Params& p, int item, unsigned char* lds) {
;     ...
;             for (int e = 0; e < 4; ++e) { const int i = it * 16 + fq * 4 + e; lv[e] = (i > j) ? bts[i] * kk[jt][e] * __expf(gcs[i] - gj) : 0.f; }
;             *(f32x4*)(lowT + j * 68 + it * 16 + fq * 4) = lv;
;             const int i2 = it * 16 + fr; const float gi = gcs[i2];
;             f32x4 av;
; #pragma unroll
;             for (int e = 0; e < 4; ++e) { const int j2 = jt * 16 + fq * 4 + e; av[e] = (i2 >= j2) ? qk[jt][e] * __expf(gi - gcs[j2]) : 0.f; }
	s_waitcnt lgkmcnt(0)
	v_sub_f32_e32 v30, v94, v46
	v_mul_f32_e32 v30, 0x3fb8aa3b, v30
	v_exp_f32_e32 v30, v30
	v_mul_f32_e32 v31, v33, v95
	v_mul_f32_e32 v37, v31, v30
.LBB0_519:
	s_or_b64 exec, exec, s[4:5]
	v_lshlrev_b32_e32 v31, 2, v45
	v_lshlrev_b32_e32 v32, 2, v40
	v_mul_u32_u24_e32 v30, 0x110, v145
	v_add3_u32 v31, s39, v31, v32
	s_waitcnt lgkmcnt(0)
	v_add_u32_e32 v46, v31, v30
	v_lshl_add_u32 v45, v39, 2, s39
	ds_write_b128 v46, v[34:37]
	ds_read_b32 v30, v45 offset:52224
	v_cmp_ge_i32_e32 vcc, v39, v40
	s_and_saveexec_b64 s[4:5], vcc
	s_cbranch_execz .LBB0_521
	v_lshl_add_u32 v31, v40, 2, s39

; DEV void gdn_prep_chunk(const Params& p, int item, unsigned char* lds) {
;     ...
;             for (int e = 0; e < 4; ++e) { const int j2 = jt * 16 + fq * 4 + e; av[e] = (i2 >= j2) ? qk[jt][e] * __expf(gi - gcs[j2]) : 0.f; }
	s_waitcnt lgkmcnt(0)
	v_sub_f32_e32 v31, v30, v98
	v_mul_f32_e32 v31, 0x3fb8aa3b, v31
	v_exp_f32_e32 v31, v31
	s_nop 0
	v_mul_f32_e32 v47, v26, v31
.LBB0_521:
	s_or_b64 exec, exec, s[4:5]
	v_cmp_gt_i32_e32 vcc, v39, v40
	v_mov_b32_e32 v35, 0
	v_mov_b32_e32 v36, 0
	s_and_saveexec_b64 s[4:5], vcc
	s_cbranch_execz .LBB0_523
	v_lshl_add_u32 v26, v40, 2, s39

; DEV void gdn_prep_chunk(const Params& p, int item, unsigned char* lds) {
;     ...
;             for (int e = 0; e < 4; ++e) { const int j2 = jt * 16 + fq * 4 + e; av[e] = (i2 >= j2) ? qk[jt][e] * __expf(gi - gcs[j2]) : 0.f; }
	s_waitcnt lgkmcnt(0)
	v_sub_f32_e32 v26, v30, v101
	v_mul_f32_e32 v26, 0x3fb8aa3b, v26
	v_exp_f32_e32 v26, v26
	s_nop 0
	v_mul_f32_e32 v36, v27, v26
.LBB0_523:
	s_or_b64 exec, exec, s[4:5]
	v_or_b32_e32 v26, 2, v40
	v_cmp_ge_i32_e32 vcc, v39, v26
	s_and_saveexec_b64 s[4:5], vcc
	s_cbranch_execz .LBB0_525
	v_lshl_add_u32 v26, v40, 2, s39

; DEV void gdn_prep_chunk(const Params& p, int item, unsigned char* lds) {
;     ...
;             for (int e = 0; e < 4; ++e) { const int j2 = jt * 16 + fq * 4 + e; av[e] = (i2 >= j2) ? qk[jt][e] * __expf(gi - gcs[j2]) : 0.f; }
	s_waitcnt lgkmcnt(0)
	v_sub_f32_e32 v26, v30, v104
	v_mul_f32_e32 v26, 0x3fb8aa3b, v26
	v_exp_f32_e32 v26, v26
	s_nop 0
	v_mul_f32_e32 v35, v28, v26
.LBB0_525:
	s_or_b64 exec, exec, s[4:5]
	v_or_b32_e32 v26, 3, v40
	v_cmp_ge_i32_e32 vcc, v39, v26
	v_mov_b32_e32 v26, 0
	v_mov_b32_e32 v27, 0
	s_and_saveexec_b64 s[4:5], vcc
	s_cbranch_execz .LBB0_527
	v_lshl_add_u32 v27, v40, 2, s39

; DEV void store_bf4(bf16_t* p, f32x4 v) { uint2 w; w.x = cvt_pk_bf16(v[0], v[1]); w.y = cvt_pk_bf16(v[2], v[3]); *(uint2*)p = w; }
; DEV void gdn_prep_chunk(const Params& p, int item, unsigned char* lds) {
;     ...
;             const int j = jt * 16 + fr; const float gj = gcs[j];
;             f32x4 lv;
; #pragma unroll
;             for (int e = 0; e < 4; ++e) { const int i = it * 16 + fq * 4 + e; lv[e] = (i > j) ? bts[i] * kk[jt][e] * __expf(gcs[i] - gj) : 0.f; }
;     ...
;             for (int e = 0; e < 4; ++e) { const int j2 = jt * 16 + fq * 4 + e; av[e] = (i2 >= j2) ? qk[jt][e] * __expf(gi - gcs[j2]) : 0.f; }
;             store_bf4(gA + (jt >> 1) * 2048 + i2 * 32 + (jt & 1) * 16 + fq * 4, av);
	s_waitcnt lgkmcnt(0)
	v_sub_f32_e32 v27, v30, v107
	v_mul_f32_e32 v27, 0x3fb8aa3b, v27
	v_exp_f32_e32 v27, v27
	s_nop 0
	v_mul_f32_e32 v27, v29, v27
.LBB0_527:
	s_or_b64 exec, exec, s[4:5]
	s_lshl_b64 s[4:5], s[30:31], 13
	ds_read_b32 v34, v43 offset:52288
	s_add_u32 s6, s49, s4
	s_waitcnt lgkmcnt(1)
	v_lshlrev_b32_e32 v30, 5, v39
	s_addc_u32 s7, s50, s5
	v_ashrrev_i32_e32 v31, 31, v30
	v_or_b32_e32 v29, 16, v145
	v_lshl_add_u64 v[30:31], v[30:31], 1, s[6:7]
	v_lshlrev_b32_e32 v142, 1, v40
	v_lshl_add_u64 v[32:33], v[30:31], 0, v[142:143]
	v_cvt_pk_bf16_f32 v36, v47, v36
	v_cvt_pk_bf16_f32 v37, v35, v27
	v_cmp_gt_i32_e32 vcc, v41, v29
	global_store_dwordx2 v[32:33], v[36:37], off
	s_and_saveexec_b64 s[6:7], vcc
	s_cbranch_execz .LBB0_529
	v_lshl_add_u32 v26, v41, 2, s39

; DEV void gdn_prep_chunk(const Params& p, int item, unsigned char* lds) {
;     ...
;             for (int e = 0; e < 4; ++e) { const int i = it * 16 + fq * 4 + e; lv[e] = (i > j) ? bts[i] * kk[jt][e] * __expf(gcs[i] - gj) : 0.f; }
	s_waitcnt lgkmcnt(0)
	v_sub_f32_e32 v26, v112, v34
	v_mul_f32_e32 v26, 0x3fb8aa3b, v26
	v_exp_f32_e32 v26, v26
	v_mul_f32_e32 v22, v22, v113
	v_mul_f32_e32 v26, v22, v26
.LBB0_529:
	s_or_b64 exec, exec, s[6:7]
	v_cmp_ge_i32_e32 vcc, v41, v29
	v_mov_b32_e32 v28, 0
	v_mov_b32_e32 v27, 0
	s_and_saveexec_b64 s[6:7], vcc
	s_cbranch_execz .LBB0_531
	v_lshl_add_u32 v22, v41, 2, s39
	v_add_u32_e32 v22, 4, v22

; DEV void gdn_prep_chunk(const Params& p, int item, unsigned char* lds) {
;     ...
;             const int j = jt * 16 + fr; const float gj = gcs[j];
;             f32x4 lv;
; #pragma unroll
;             for (int e = 0; e < 4; ++e) { const int i = it * 16 + fq * 4 + e; lv[e] = (i > j) ? bts[i] * kk[jt][e] * __expf(gcs[i] - gj) : 0.f; }
;             *(f32x4*)(lowT + j * 68 + it * 16 + fq * 4) = lv;
	s_waitcnt lgkmcnt(0)
	v_sub_f32_e32 v22, v118, v34
	v_mul_f32_e32 v22, 0x3fb8aa3b, v22
	v_exp_f32_e32 v22, v22
	v_mul_f32_e32 v23, v23, v119
	v_mul_f32_e32 v27, v23, v22
.LBB0_531:
	s_or_b64 exec, exec, s[6:7]
	v_cmp_gt_i32_e32 vcc, v42, v29
	s_and_saveexec_b64 s[6:7], vcc
	s_cbranch_execz .LBB0_533
	v_lshl_add_u32 v22, v41, 2, s39
	v_add_u32_e32 v22, 8, v22

; DEV void gdn_prep_chunk(const Params& p, int item, unsigned char* lds) {
;     ...
;             const int j = jt * 16 + fr; const float gj = gcs[j];
;             f32x4 lv;
; #pragma unroll
;             for (int e = 0; e < 4; ++e) { const int i = it * 16 + fq * 4 + e; lv[e] = (i > j) ? bts[i] * kk[jt][e] * __expf(gcs[i] - gj) : 0.f; }
;             *(f32x4*)(lowT + j * 68 + it * 16 + fq * 4) = lv;
	s_waitcnt lgkmcnt(0)
	v_sub_f32_e32 v22, v124, v34
	v_mul_f32_e32 v22, 0x3fb8aa3b, v22
	v_exp_f32_e32 v22, v22
	v_mul_f32_e32 v23, v24, v125
	v_mul_f32_e32 v28, v23, v22

; DEV void gdn_prep_chunk(const Params& p, int item, unsigned char* lds) {
;     ...
;             for (int e = 0; e < 4; ++e) { const int i = it * 16 + fq * 4 + e; lv[e] = (i > j) ? bts[i] * kk[jt][e] * __expf(gcs[i] - gj) : 0.f; }
;             *(f32x4*)(lowT + j * 68 + it * 16 + fq * 4) = lv;
;             const int i2 = it * 16 + fr; const float gi = gcs[i2];
;             f32x4 av;
; #pragma unroll
;             for (int e = 0; e < 4; ++e) { const int j2 = jt * 16 + fq * 4 + e; av[e] = (i2 >= j2) ? qk[jt][e] * __expf(gi - gcs[j2]) : 0.f; }
.LBB0_535:
	s_or_b64 exec, exec, s[6:7]
	ds_write_b128 v46, v[26:29] offset:4352
	ds_read_b32 v23, v45 offset:52224
	v_or_b32_e32 v24, 16, v40
	v_cmp_ge_i32_e32 vcc, v39, v24
	s_and_saveexec_b64 s[6:7], vcc
	s_cbranch_execz .LBB0_537
	v_lshl_add_u32 v22, v40, 2, s39

; DEV void gdn_prep_chunk(const Params& p, int item, unsigned char* lds) {
;     ...
;             const int i2 = it * 16 + fr; const float gi = gcs[i2];
;             f32x4 av;
; #pragma unroll
;             for (int e = 0; e < 4; ++e) { const int j2 = jt * 16 + fq * 4 + e; av[e] = (i2 >= j2) ? qk[jt][e] * __expf(gi - gcs[j2]) : 0.f; }
	s_waitcnt lgkmcnt(0)
	v_sub_f32_e32 v22, v23, v128
	v_mul_f32_e32 v22, 0x3fb8aa3b, v22
	v_exp_f32_e32 v22, v22
	s_nop 0
	v_mul_f32_e32 v22, v18, v22
.LBB0_537:
	s_or_b64 exec, exec, s[6:7]
	v_or_b32_e32 v18, 17, v40
	v_cmp_ge_i32_e32 vcc, v39, v18
	v_mov_b32_e32 v24, 0
	v_mov_b32_e32 v25, 0
	s_and_saveexec_b64 s[6:7], vcc
	s_cbranch_execz .LBB0_539
	v_lshl_add_u32 v18, v40, 2, s39

; DEV void gdn_prep_chunk(const Params& p, int item, unsigned char* lds) {
;     ...
;             const int i2 = it * 16 + fr; const float gi = gcs[i2];
;             f32x4 av;
; #pragma unroll
;             for (int e = 0; e < 4; ++e) { const int j2 = jt * 16 + fq * 4 + e; av[e] = (i2 >= j2) ? qk[jt][e] * __expf(gi - gcs[j2]) : 0.f; }
	s_waitcnt lgkmcnt(0)
	v_sub_f32_e32 v18, v23, v190
	v_mul_f32_e32 v18, 0x3fb8aa3b, v18
	v_exp_f32_e32 v18, v18
	s_nop 0
	v_mul_f32_e32 v25, v19, v18
.LBB0_539:
	s_or_b64 exec, exec, s[6:7]
	v_or_b32_e32 v18, 18, v40
	v_cmp_ge_i32_e32 vcc, v39, v18
	s_and_saveexec_b64 s[6:7], vcc
	s_cbranch_execz .LBB0_541
	v_lshl_add_u32 v18, v40, 2, s39

; DEV void gdn_prep_chunk(const Params& p, int item, unsigned char* lds) {
;     ...
;             const int i2 = it * 16 + fr; const float gi = gcs[i2];
;             f32x4 av;
; #pragma unroll
;             for (int e = 0; e < 4; ++e) { const int j2 = jt * 16 + fq * 4 + e; av[e] = (i2 >= j2) ? qk[jt][e] * __expf(gi - gcs[j2]) : 0.f; }
	s_waitcnt lgkmcnt(0)
	v_sub_f32_e32 v18, v23, v193
	v_mul_f32_e32 v18, 0x3fb8aa3b, v18
	v_exp_f32_e32 v18, v18
	s_nop 0
	v_mul_f32_e32 v24, v20, v18
.LBB0_541:
	s_or_b64 exec, exec, s[6:7]
	v_or_b32_e32 v18, 19, v40
	v_cmp_ge_i32_e32 vcc, v39, v18
	v_mov_b32_e32 v18, 0
	v_mov_b32_e32 v19, 0
	s_and_saveexec_b64 s[6:7], vcc
	s_cbranch_execz .LBB0_543
	v_lshl_add_u32 v19, v40, 2, s39

; DEV void store_bf4(bf16_t* p, f32x4 v) { uint2 w; w.x = cvt_pk_bf16(v[0], v[1]); w.y = cvt_pk_bf16(v[2], v[3]); *(uint2*)p = w; }
; DEV void gdn_prep_chunk(const Params& p, int item, unsigned char* lds) {
;     ...
;             const int j = jt * 16 + fr; const float gj = gcs[j];
;     ...
;             const int i2 = it * 16 + fr; const float gi = gcs[i2];
;             f32x4 av;
; #pragma unroll
;             for (int e = 0; e < 4; ++e) { const int j2 = jt * 16 + fq * 4 + e; av[e] = (i2 >= j2) ? qk[jt][e] * __expf(gi - gcs[j2]) : 0.f; }
;             store_bf4(gA + (jt >> 1) * 2048 + i2 * 32 + (jt & 1) * 16 + fq * 4, av);
	s_waitcnt lgkmcnt(0)
	v_sub_f32_e32 v19, v23, v196
	v_mul_f32_e32 v19, 0x3fb8aa3b, v19
	v_exp_f32_e32 v19, v19
	s_nop 0
	v_mul_f32_e32 v19, v21, v19
.LBB0_543:
	s_or_b64 exec, exec, s[6:7]
	s_waitcnt lgkmcnt(0)
	ds_read_b32 v23, v43 offset:52352
	v_or_b32_e32 v21, 32, v145
	v_cvt_pk_bf16_f32 v26, v22, v25
	v_cvt_pk_bf16_f32 v27, v24, v19
	v_cmp_gt_i32_e32 vcc, v41, v21
	global_store_dwordx2 v[32:33], v[26:27], off offset:32
	s_and_saveexec_b64 s[6:7], vcc
	s_cbranch_execz .LBB0_545
	v_lshl_add_u32 v18, v41, 2, s39

; DEV void gdn_prep_chunk(const Params& p, int item, unsigned char* lds) {
;     ...
;             const int j = jt * 16 + fr; const float gj = gcs[j];
;             f32x4 lv;
; #pragma unroll
;             for (int e = 0; e < 4; ++e) { const int i = it * 16 + fq * 4 + e; lv[e] = (i > j) ? bts[i] * kk[jt][e] * __expf(gcs[i] - gj) : 0.f; }
;             *(f32x4*)(lowT + j * 68 + it * 16 + fq * 4) = lv;
	s_waitcnt lgkmcnt(0)
	v_sub_f32_e32 v18, v200, v23
	v_mul_f32_e32 v18, 0x3fb8aa3b, v18
	v_exp_f32_e32 v18, v18
	v_mul_f32_e32 v14, v14, v201
	v_mul_f32_e32 v18, v14, v18
.LBB0_545:
	s_or_b64 exec, exec, s[6:7]
	v_cmp_ge_i32_e32 vcc, v41, v21
	v_mov_b32_e32 v20, 0
	v_mov_b32_e32 v19, 0
	s_and_saveexec_b64 s[6:7], vcc
	s_cbranch_execz .LBB0_547
	v_lshl_add_u32 v14, v41, 2, s39
	v_add_u32_e32 v14, 4, v14

; DEV void gdn_prep_chunk(const Params& p, int item, unsigned char* lds) {
;     ...
;             const int j = jt * 16 + fr; const float gj = gcs[j];
;             f32x4 lv;
; #pragma unroll
;             for (int e = 0; e < 4; ++e) { const int i = it * 16 + fq * 4 + e; lv[e] = (i > j) ? bts[i] * kk[jt][e] * __expf(gcs[i] - gj) : 0.f; }
;             *(f32x4*)(lowT + j * 68 + it * 16 + fq * 4) = lv;
	s_waitcnt lgkmcnt(0)
	v_sub_f32_e32 v14, v206, v23
	v_mul_f32_e32 v14, 0x3fb8aa3b, v14
	v_exp_f32_e32 v14, v14
	v_mul_f32_e32 v15, v15, v207
	v_mul_f32_e32 v19, v15, v14
.LBB0_547:
	s_or_b64 exec, exec, s[6:7]
	v_cmp_gt_i32_e32 vcc, v42, v21
	s_and_saveexec_b64 s[6:7], vcc
	s_cbranch_execz .LBB0_549
	v_lshl_add_u32 v14, v41, 2, s39
	v_add_u32_e32 v14, 8, v14

; DEV void gdn_prep_chunk(const Params& p, int item, unsigned char* lds) {
;     ...
;             const int j = jt * 16 + fr; const float gj = gcs[j];
;             f32x4 lv;
; #pragma unroll
;             for (int e = 0; e < 4; ++e) { const int i = it * 16 + fq * 4 + e; lv[e] = (i > j) ? bts[i] * kk[jt][e] * __expf(gcs[i] - gj) : 0.f; }
;             *(f32x4*)(lowT + j * 68 + it * 16 + fq * 4) = lv;
	s_waitcnt lgkmcnt(0)
	v_sub_f32_e32 v14, v212, v23
	v_mul_f32_e32 v14, 0x3fb8aa3b, v14
	v_exp_f32_e32 v14, v14
	v_mul_f32_e32 v15, v16, v213
	v_mul_f32_e32 v20, v15, v14

; DEV void gdn_prep_chunk(const Params& p, int item, unsigned char* lds) {
;     ...
;             for (int e = 0; e < 4; ++e) { const int i = it * 16 + fq * 4 + e; lv[e] = (i > j) ? bts[i] * kk[jt][e] * __expf(gcs[i] - gj) : 0.f; }
;             *(f32x4*)(lowT + j * 68 + it * 16 + fq * 4) = lv;
;             const int i2 = it * 16 + fr; const float gi = gcs[i2];
;             f32x4 av;
; #pragma unroll
;             for (int e = 0; e < 4; ++e) { const int j2 = jt * 16 + fq * 4 + e; av[e] = (i2 >= j2) ? qk[jt][e] * __expf(gi - gcs[j2]) : 0.f; }
.LBB0_551:
	s_or_b64 exec, exec, s[6:7]
	ds_write_b128 v46, v[18:21] offset:8704
	ds_read_b32 v15, v45 offset:52224
	v_or_b32_e32 v16, 32, v40
	v_cmp_ge_i32_e32 vcc, v39, v16
	s_and_saveexec_b64 s[6:7], vcc
	s_cbranch_execz .LBB0_553
	v_lshl_add_u32 v14, v40, 2, s39

; DEV void gdn_prep_chunk(const Params& p, int item, unsigned char* lds) {
;     ...
;             const int i2 = it * 16 + fr; const float gi = gcs[i2];
;             f32x4 av;
; #pragma unroll
;             for (int e = 0; e < 4; ++e) { const int j2 = jt * 16 + fq * 4 + e; av[e] = (i2 >= j2) ? qk[jt][e] * __expf(gi - gcs[j2]) : 0.f; }
	s_waitcnt lgkmcnt(0)
	v_sub_f32_e32 v14, v15, v216
	v_mul_f32_e32 v14, 0x3fb8aa3b, v14
	v_exp_f32_e32 v14, v14
	s_nop 0
	v_mul_f32_e32 v14, v10, v14
.LBB0_553:
	s_or_b64 exec, exec, s[6:7]
	v_or_b32_e32 v10, 33, v40
	v_cmp_ge_i32_e32 vcc, v39, v10
	v_mov_b32_e32 v16, 0
	v_mov_b32_e32 v17, 0
	s_and_saveexec_b64 s[6:7], vcc
	s_cbranch_execz .LBB0_555
	v_lshl_add_u32 v10, v40, 2, s39

; DEV void gdn_prep_chunk(const Params& p, int item, unsigned char* lds) {
;     ...
;             const int i2 = it * 16 + fr; const float gi = gcs[i2];
;             f32x4 av;
; #pragma unroll
;             for (int e = 0; e < 4; ++e) { const int j2 = jt * 16 + fq * 4 + e; av[e] = (i2 >= j2) ? qk[jt][e] * __expf(gi - gcs[j2]) : 0.f; }
	s_waitcnt lgkmcnt(0)
	v_sub_f32_e32 v10, v15, v219
	v_mul_f32_e32 v10, 0x3fb8aa3b, v10
	v_exp_f32_e32 v10, v10
	s_nop 0
	v_mul_f32_e32 v17, v11, v10
.LBB0_555:
	s_or_b64 exec, exec, s[6:7]
	v_or_b32_e32 v10, 34, v40
	v_cmp_ge_i32_e32 vcc, v39, v10
	s_and_saveexec_b64 s[6:7], vcc
	s_cbranch_execz .LBB0_557
	v_lshl_add_u32 v10, v40, 2, s39

; DEV void gdn_prep_chunk(const Params& p, int item, unsigned char* lds) {
;     ...
;             const int i2 = it * 16 + fr; const float gi = gcs[i2];
;             f32x4 av;
; #pragma unroll
;             for (int e = 0; e < 4; ++e) { const int j2 = jt * 16 + fq * 4 + e; av[e] = (i2 >= j2) ? qk[jt][e] * __expf(gi - gcs[j2]) : 0.f; }
	s_waitcnt lgkmcnt(0)
	v_sub_f32_e32 v10, v15, v222
	v_mul_f32_e32 v10, 0x3fb8aa3b, v10
	v_exp_f32_e32 v10, v10
	s_nop 0
	v_mul_f32_e32 v16, v12, v10
.LBB0_557:
	s_or_b64 exec, exec, s[6:7]
	v_or_b32_e32 v10, 35, v40
	v_cmp_ge_i32_e32 vcc, v39, v10
	v_mov_b32_e32 v10, 0
	v_mov_b32_e32 v11, 0
	s_and_saveexec_b64 s[6:7], vcc
	s_cbranch_execz .LBB0_559
	v_lshl_add_u32 v11, v40, 2, s39

; DEV void store_bf4(bf16_t* p, f32x4 v) { uint2 w; w.x = cvt_pk_bf16(v[0], v[1]); w.y = cvt_pk_bf16(v[2], v[3]); *(uint2*)p = w; }
; DEV void gdn_prep_chunk(const Params& p, int item, unsigned char* lds) {
;     ...
;             const int j = jt * 16 + fr; const float gj = gcs[j];
;     ...
;             const int i2 = it * 16 + fr; const float gi = gcs[i2];
;             f32x4 av;
; #pragma unroll
;             for (int e = 0; e < 4; ++e) { const int j2 = jt * 16 + fq * 4 + e; av[e] = (i2 >= j2) ? qk[jt][e] * __expf(gi - gcs[j2]) : 0.f; }
;             store_bf4(gA + (jt >> 1) * 2048 + i2 * 32 + (jt & 1) * 16 + fq * 4, av);
	s_waitcnt lgkmcnt(0)
	v_sub_f32_e32 v11, v15, v225
	v_mul_f32_e32 v11, 0x3fb8aa3b, v11
	v_exp_f32_e32 v11, v11
	s_nop 0
	v_mul_f32_e32 v11, v13, v11
.LBB0_559:
	s_or_b64 exec, exec, s[6:7]
	v_cvt_pk_bf16_f32 v20, v14, v17
	ds_read_b32 v14, v43 offset:52416
	v_lshl_add_u64 v[18:19], v[30:31], 0, v[142:143]
	v_cvt_pk_bf16_f32 v21, v16, v11
	v_add_co_u32_e32 v16, vcc, 0x1000, v18
	v_or_b32_e32 v13, 48, v145
	s_nop 0
	v_addc_co_u32_e32 v17, vcc, 0, v19, vcc
	v_cmp_gt_i32_e32 vcc, v41, v13
	global_store_dwordx2 v[16:17], v[20:21], off
	s_and_saveexec_b64 s[6:7], vcc
	s_cbranch_execz .LBB0_561
	v_lshl_add_u32 v10, v41, 2, s39

; DEV void gdn_prep_chunk(const Params& p, int item, unsigned char* lds) {
;     ...
;             const int j = jt * 16 + fr; const float gj = gcs[j];
;             f32x4 lv;
; #pragma unroll
;             for (int e = 0; e < 4; ++e) { const int i = it * 16 + fq * 4 + e; lv[e] = (i > j) ? bts[i] * kk[jt][e] * __expf(gcs[i] - gj) : 0.f; }
;             *(f32x4*)(lowT + j * 68 + it * 16 + fq * 4) = lv;
	s_waitcnt lgkmcnt(0)
	v_sub_f32_e32 v10, v230, v14
	v_mul_f32_e32 v10, 0x3fb8aa3b, v10
	v_exp_f32_e32 v10, v10
	v_mul_f32_e32 v6, v6, v231
	v_mul_f32_e32 v10, v6, v10
.LBB0_561:
	s_or_b64 exec, exec, s[6:7]
	v_cmp_ge_i32_e32 vcc, v41, v13
	v_mov_b32_e32 v12, 0
	v_mov_b32_e32 v11, 0
	s_and_saveexec_b64 s[6:7], vcc
	s_cbranch_execz .LBB0_563
	v_lshl_add_u32 v6, v41, 2, s39
	v_add_u32_e32 v6, 4, v6

; DEV void gdn_prep_chunk(const Params& p, int item, unsigned char* lds) {
;     ...
;             const int j = jt * 16 + fr; const float gj = gcs[j];
;             f32x4 lv;
; #pragma unroll
;             for (int e = 0; e < 4; ++e) { const int i = it * 16 + fq * 4 + e; lv[e] = (i > j) ? bts[i] * kk[jt][e] * __expf(gcs[i] - gj) : 0.f; }
;             *(f32x4*)(lowT + j * 68 + it * 16 + fq * 4) = lv;
	s_waitcnt lgkmcnt(0)
	v_sub_f32_e32 v6, v236, v14
	v_mul_f32_e32 v6, 0x3fb8aa3b, v6
	v_exp_f32_e32 v6, v6
	v_mul_f32_e32 v7, v7, v237
	v_mul_f32_e32 v11, v7, v6
.LBB0_563:
	s_or_b64 exec, exec, s[6:7]
	v_cmp_gt_i32_e32 vcc, v42, v13
	s_and_saveexec_b64 s[6:7], vcc
	s_cbranch_execz .LBB0_565
	v_lshl_add_u32 v6, v41, 2, s39
	v_add_u32_e32 v6, 8, v6

; DEV void gdn_prep_chunk(const Params& p, int item, unsigned char* lds) {
;     ...
;             const int j = jt * 16 + fr; const float gj = gcs[j];
;             f32x4 lv;
; #pragma unroll
;             for (int e = 0; e < 4; ++e) { const int i = it * 16 + fq * 4 + e; lv[e] = (i > j) ? bts[i] * kk[jt][e] * __expf(gcs[i] - gj) : 0.f; }
;             *(f32x4*)(lowT + j * 68 + it * 16 + fq * 4) = lv;
	s_waitcnt lgkmcnt(0)
	v_sub_f32_e32 v6, v242, v14
	v_mul_f32_e32 v6, 0x3fb8aa3b, v6
	v_exp_f32_e32 v6, v6
	v_mul_f32_e32 v7, v8, v243
	v_mul_f32_e32 v12, v7, v6

; DEV void gdn_prep_chunk(const Params& p, int item, unsigned char* lds) {
;     ...
;             for (int e = 0; e < 4; ++e) { const int i = it * 16 + fq * 4 + e; lv[e] = (i > j) ? bts[i] * kk[jt][e] * __expf(gcs[i] - gj) : 0.f; }
;             *(f32x4*)(lowT + j * 68 + it * 16 + fq * 4) = lv;
;             const int i2 = it * 16 + fr; const float gi = gcs[i2];
;             f32x4 av;
; #pragma unroll
;             for (int e = 0; e < 4; ++e) { const int j2 = jt * 16 + fq * 4 + e; av[e] = (i2 >= j2) ? qk[jt][e] * __expf(gi - gcs[j2]) : 0.f; }
.LBB0_567:
	s_or_b64 exec, exec, s[6:7]
	ds_write_b128 v46, v[10:13] offset:13056
	ds_read_b32 v7, v45 offset:52224
	v_or_b32_e32 v8, 48, v40
	v_cmp_ge_i32_e32 vcc, v39, v8
	s_and_saveexec_b64 s[6:7], vcc
	s_cbranch_execz .LBB0_569
	v_lshl_add_u32 v6, v40, 2, s39

; DEV void gdn_prep_chunk(const Params& p, int item, unsigned char* lds) {
;     ...
;             const int i2 = it * 16 + fr; const float gi = gcs[i2];
;             f32x4 av;
; #pragma unroll
;             for (int e = 0; e < 4; ++e) { const int j2 = jt * 16 + fq * 4 + e; av[e] = (i2 >= j2) ? qk[jt][e] * __expf(gi - gcs[j2]) : 0.f; }
	s_waitcnt lgkmcnt(0)
	v_sub_f32_e32 v6, v7, v246
	v_mul_f32_e32 v6, 0x3fb8aa3b, v6
	v_exp_f32_e32 v6, v6
	s_nop 0
	v_mul_f32_e32 v6, v2, v6
.LBB0_569:
	s_or_b64 exec, exec, s[6:7]
	v_or_b32_e32 v2, 49, v40
	v_cmp_ge_i32_e32 vcc, v39, v2
	v_mov_b32_e32 v2, 0
	v_mov_b32_e32 v8, 0
	s_and_saveexec_b64 s[6:7], vcc
	s_cbranch_execz .LBB0_571
	v_lshl_add_u32 v8, v40, 2, s39

; DEV void gdn_prep_chunk(const Params& p, int item, unsigned char* lds) {
;     ...
;             const int i2 = it * 16 + fr; const float gi = gcs[i2];
;             f32x4 av;
; #pragma unroll
;             for (int e = 0; e < 4; ++e) { const int j2 = jt * 16 + fq * 4 + e; av[e] = (i2 >= j2) ? qk[jt][e] * __expf(gi - gcs[j2]) : 0.f; }
	s_waitcnt lgkmcnt(0)
	v_sub_f32_e32 v8, v7, v249
	v_mul_f32_e32 v8, 0x3fb8aa3b, v8
	v_exp_f32_e32 v8, v8
	s_nop 0
	v_mul_f32_e32 v8, v3, v8
.LBB0_571:
	s_or_b64 exec, exec, s[6:7]
	v_or_b32_e32 v3, 50, v40
	v_cmp_ge_i32_e32 vcc, v39, v3
	s_and_saveexec_b64 s[6:7], vcc
	s_cbranch_execz .LBB0_573
	v_lshl_add_u32 v2, v40, 2, s39

; DEV void gdn_prep_chunk(const Params& p, int item, unsigned char* lds) {
;     ...
;             const int i2 = it * 16 + fr; const float gi = gcs[i2];
;             f32x4 av;
; #pragma unroll
;             for (int e = 0; e < 4; ++e) { const int j2 = jt * 16 + fq * 4 + e; av[e] = (i2 >= j2) ? qk[jt][e] * __expf(gi - gcs[j2]) : 0.f; }
	s_waitcnt lgkmcnt(0)
	v_sub_f32_e32 v2, v7, v146
	v_mul_f32_e32 v2, 0x3fb8aa3b, v2
	v_exp_f32_e32 v2, v2
	s_nop 0
	v_mul_f32_e32 v2, v4, v2
.LBB0_573:
	s_or_b64 exec, exec, s[6:7]
	v_or_b32_e32 v3, 51, v40
	v_cmp_ge_i32_e32 vcc, v39, v3
	v_mov_b32_e32 v3, 0
	s_and_saveexec_b64 s[6:7], vcc
	s_cbranch_execz .LBB0_575
	v_lshl_add_u32 v3, v40, 2, s39

; DEV void gdn_prep_chunk(const Params& p, int item, unsigned char* lds) {
;     ...
;             const int i2 = it * 16 + fr; const float gi = gcs[i2];
;             f32x4 av;
; #pragma unroll
;             for (int e = 0; e < 4; ++e) { const int j2 = jt * 16 + fq * 4 + e; av[e] = (i2 >= j2) ? qk[jt][e] * __expf(gi - gcs[j2]) : 0.f; }
	s_waitcnt lgkmcnt(0)
	v_sub_f32_e32 v3, v7, v149
	v_mul_f32_e32 v3, 0x3fb8aa3b, v3
	v_exp_f32_e32 v3, v3
	s_nop 0
	v_mul_f32_e32 v3, v5, v3
